# w_uq fp32-to-bf16 conversion item: 8 weight rows and 8 gains loaded together (was one load per wait), on top of v046
# speedup vs baseline: 1.0052x; 1.0052x over previous
; DI u16 bf1(float x) { return (u16)(pk2(x, 0.f) & 0xffffu); }
; DI void conv_tile(unsigned char* smem, const int wv, const float* __restrict__ src, u16* __restrict__ dst, int K, int N, int kind, const float* __restrict__ gain, int ktile, int ntile, bool kperm = false) {
;     ...
;   for (int i = 0; i < 8; ++i) {
;     const int k = kq * 8 + i;
;     float v = 0.f;
;     if (n < N) { v = src[(size_t)(k0 + k) * N + n]; if (gain) v *= gain[k0 + k]; }
;     T[nl][k] = bf1(v);
;   }
.LBB0_982:
	v_readlane_b32 s0, v252, 63
	v_readlane_b32 s1, v253, 0
	s_mov_b64 s[2:3], 0x1800
	v_lshl_add_u64 v[206:207], v[2:3], 0, s[2:3]
	v_lshl_add_u64 v[208:209], v[206:207], 0, s[2:3]
	v_lshl_add_u64 v[224:225], v[208:209], 0, s[2:3]
	global_load_dword v212, v[2:3], off
	global_load_dword v213, v[2:3], off offset:3072
	global_load_dword v214, v[206:207], off
	global_load_dword v215, v[206:207], off offset:3072
	global_load_dword v216, v[208:209], off
	global_load_dword v217, v[208:209], off offset:3072
	global_load_dword v218, v[224:225], off
	global_load_dword v219, v[224:225], off offset:3072
	v_cndmask_b32_e64 v103, 0, 1, s[0:1]
	v_cmp_ne_u32_e64 s[92:93], 1, v103
	s_andn2_b64 vcc, exec, s[0:1]
	s_cbranch_vccnz .Lconv4_cvt
	global_load_dword v220, v[100:101], off
	global_load_dword v221, v[0:1], off offset:4
	global_load_dword v222, v[0:1], off offset:8
	global_load_dword v223, v[0:1], off offset:12
	global_load_dword v226, v[100:101], off offset:16
	global_load_dword v227, v[0:1], off offset:20
	global_load_dword v206, v[0:1], off offset:24
	global_load_dword v207, v[0:1], off offset:28
	s_waitcnt vmcnt(0)
	v_mul_f32_e32 v212, v212, v220
	v_mul_f32_e32 v213, v213, v221
	v_mul_f32_e32 v214, v214, v222
	v_mul_f32_e32 v215, v215, v223
	v_mul_f32_e32 v216, v216, v226
	v_mul_f32_e32 v217, v217, v227
	v_mul_f32_e32 v218, v218, v206
	v_mul_f32_e32 v219, v219, v207
.Lconv4_cvt:
	s_waitcnt vmcnt(0)
	v_cvt_pk_bf16_f32 v220, v212, v213
	v_cvt_pk_bf16_f32 v221, v214, v215
	v_cvt_pk_bf16_f32 v222, v216, v217
	v_cvt_pk_bf16_f32 v223, v218, v219
	ds_write_b32 v183, v220
	ds_write_b32 v183, v221 offset:4
	ds_write_b32 v183, v222 offset:8
	ds_write_b32 v183, v223 offset:12
	v_add_u32_e32 v183, 16, v183
	s_mov_b64 s[0:1], 0x3000
	s_mov_b64 s[2:3], 32
